# static s_setprio 1 for waves 4-7 during the mixer phases (mix1 + rout), reset before merge
# speedup vs baseline: 1.0063x; 1.0062x over previous
; #define LAS __attribute__((address_space(3)))
; __device__ __forceinline__ void scan_item(const Args& a, int l, int it, LAS unsigned char* lds, int tid) {
;     ...
;     const int dsl = it & 3, dir = (it >> 2) & 1, bh = it >> 3, b = bh >> 2, h = bh & 3;
;     bf16_t* ST = (bf16_t*)(a.ws + (dir ? WS_SB : WS_SF)) + (size_t)bh * 32 * 65536;
;     const float lg = -expf(a.in[dir ? 4 : 3][l * 4 + h]); const float dec = expf(lg * 128.f);
;     LAS unsigned char* Ks = lds; LAS unsigned char* Vs = lds + 20480;
;     f32x4 st[4][2];
; #pragma unroll
;     for (int dt = 0; dt < 4; ++dt) { st[dt][0] = (f32x4){0.f, 0.f, 0.f, 0.f}; st[dt][1] = (f32x4){0.f, 0.f, 0.f, 0.f}; }
;     u32x4 vrA[8], krA[2], vrB[8], krB[2];
;     const bf16_t* zb = Z + (size_t)(b * SEQ) * NIN + h * 256;
.LBB0_217:
	s_andn2_b64 vcc, exec, s[2:3]
	s_cbranch_vccnz .LBB0_314
	v_readfirstlane_b32 s98, v222
	s_cmpk_gt_u32 s98, 0xff
	s_cbranch_scc0 .Lmixprio_skip
	s_setprio 1
.Lmixprio_skip:
	s_waitcnt lgkmcnt(0)
	v_mov_b32_e32 v1, v222
	s_lshl_b32 s8, s69, 2
	s_mov_b32 s9, s81
	s_lshl_b64 s[2:3], s[8:9], 2
	v_add_u32_e32 v4, 0x200, v1
	v_add_u32_e32 v6, 0x400, v1
	v_add_u32_e32 v7, 0x600, v1
	v_add_u32_e32 v8, 0x800, v1
	v_add_u32_e32 v9, 0xa00, v1
	v_add_u32_e32 v10, 0xc00, v1
	v_add_u32_e32 v11, 0xe00, v1
	v_readlane_b32 s4, v254, 34
	v_ashrrev_i32_e32 v3, 5, v1
	v_ashrrev_i32_e32 v5, 5, v4
	v_ashrrev_i32_e32 v6, 5, v6
	v_ashrrev_i32_e32 v7, 5, v7
	v_ashrrev_i32_e32 v8, 5, v8
	v_ashrrev_i32_e32 v9, 5, v9
	v_ashrrev_i32_e32 v10, 5, v10
	v_ashrrev_i32_e32 v11, 5, v11
	v_ashrrev_i32_e32 v12, 3, v1
	v_ashrrev_i32_e32 v4, 3, v4
	s_add_u32 s6, s4, s2
	v_mad_i64_i32 v[114:115], s[4:5], v3, s58, 0
	v_mad_i64_i32 v[116:117], s[4:5], v5, s58, 0
	v_mad_i64_i32 v[118:119], s[4:5], v6, s58, 0
	v_mad_i64_i32 v[120:121], s[4:5], v7, s58, 0
	v_mad_i64_i32 v[122:123], s[4:5], v8, s58, 0
	v_mad_i64_i32 v[124:125], s[4:5], v9, s58, 0
	v_mad_i64_i32 v[126:127], s[4:5], v10, s58, 0
	v_mad_i64_i32 v[128:129], s[4:5], v11, s58, 0
	v_mad_i64_i32 v[132:133], s[4:5], v12, s58, 0
	s_waitcnt lgkmcnt(0)
	v_mad_i64_i32 v[134:135], s[4:5], v4, s58, 0
	v_and_b32_e32 v0, 15, v1
	v_lshlrev_b32_e32 v2, 3, v1
	v_ashrrev_i32_e32 v15, 1, v1
	s_movk_i32 s4, 0xffe0
	v_readlane_b32 s2, v254, 35
	v_and_b32_e32 v112, 0xf8, v2
	v_and_b32_e32 v130, 56, v2
	v_and_or_b32 v0, v15, s4, v0
	v_lshrrev_b32_e32 v15, 2, v1
	v_and_b32_e32 v2, 24, v2
	s_addc_u32 s7, s2, s3
	v_cmp_eq_u32_e64 s[2:3], 0, v1
	v_lshlrev_b32_e32 v13, 4, v1
	v_and_b32_e32 v113, 12, v15
	v_bfe_u32 v15, v1, 2, 4
	v_add_u32_e32 v2, 0, v2
	v_and_b32_e32 v1, 0xffffffc0, v1
	v_add_u32_e32 v16, v2, v1
	v_sub_u32_e32 v1, 0x7f, v12
	v_cvt_f32_i32_e32 v152, v1
	v_sub_u32_e32 v1, 0x7f, v4
	v_cvt_f32_i32_e32 v154, v1
	v_ashrrev_i32_e32 v1, 31, v0
	v_cvt_f32_i32_e32 v131, v12
	v_cvt_f32_i32_e32 v153, v4
	v_lshlrev_b64 v[136:137], 9, v[0:1]
	v_or_b32_e32 v0, 16, v0
	v_and_b32_e32 v14, 0x1f0, v13
	v_and_b32_e32 v13, 0x70, v13
	s_movk_i32 s4, 0xa0
	v_ashrrev_i32_e32 v1, 31, v0
	v_mov_b32_e32 v17, 0x4400
	v_add_u32_e32 v14, 0, v14
	v_add_u32_e32 v13, 0, v13
	v_mul_lo_u32 v3, v3, s59
	v_mul_lo_u32 v5, v5, s59
	v_mul_lo_u32 v6, v6, s59
	v_mul_lo_u32 v7, v7, s59
	v_mul_lo_u32 v8, v8, s59
	v_mul_lo_u32 v9, v9, s59
	v_mul_lo_u32 v10, v10, s59
	v_mul_lo_u32 v11, v11, s59
	v_mul_lo_u32 v12, v12, s4
	v_mul_lo_u32 v4, v4, s4
	v_lshlrev_b64 v[138:139], 9, v[0:1]
	v_bfe_u32 v196, v222, 4, 1
	v_mul_u32_u24_e32 v196, 24, v196
	v_add_u32_e32 v136, v136, v196
	v_add_u32_e32 v138, v138, v196
	v_mul_u32_u24_e32 v0, 0xa0, v15
	v_mul_u32_u24_e32 v1, 0x220, v15
	v_mad_u32_u24 v15, v15, s59, v17
	v_add_u32_e32 v155, v14, v3
	v_add_u32_e32 v156, v14, v5
	v_add_u32_e32 v157, v14, v6
	v_add_u32_e32 v158, v14, v7
	v_add_u32_e32 v159, v14, v8
	v_add_u32_e32 v160, v14, v9
	v_add_u32_e32 v161, v14, v10
	v_add_u32_e32 v162, v14, v11
	v_add_u32_e32 v163, v13, v12
	v_add_u32_e32 v164, v13, v4
	v_add_u32_e32 v165, v2, v0
	v_add_u32_e32 v166, v16, v1
	v_add_u32_e32 v167, v16, v15
	s_branch .LBB0_221

; __device__ __forceinline__ void xcd_barrier(const XcdBarrier& b) {
;     asm volatile("s_waitcnt vmcnt(0)" ::: "memory");
;     __syncthreads();
;     if (threadIdx.x == 0) {
;         unsigned* bar = b.bar;
;         __builtin_amdgcn_s_waitcnt(0);
;         unsigned nloc = b.st[0], nx = b.st[1];
;         if (nloc == 0u) { xcd_barrier_complete(bar, b.x, nloc, nx); b.st[0] = nloc; b.st[1] = nx; }
.LBB0_333:
	s_setprio 0
	v_readlane_b32 s2, v255, 25
	s_add_i32 s14, s2, 4
	s_cmp_ge_i32 s14, s77
	s_cbranch_scc1 .LBB0_387
	s_getreg_b32 s4, hwreg(HW_REG_XCC_ID, 0, 4)
	s_waitcnt vmcnt(0)
	s_barrier
	s_mov_b64 s[2:3], exec
	v_readlane_b32 s6, v255, 9
	v_readlane_b32 s7, v255, 10
	s_and_b64 s[6:7], s[2:3], s[6:7]
	s_mov_b64 exec, s[6:7]
	s_cbranch_execz .LBB0_386
	v_readlane_b32 s5, v255, 1
	s_waitcnt vmcnt(0) expcnt(0) lgkmcnt(0)
	s_and_b32 s12, s4, 15
	v_mov_b32_e32 v0, s5
	ds_read_b32 v2, v0
	v_readlane_b32 s5, v255, 2
	s_waitcnt lgkmcnt(0)
	v_cmp_ne_u32_e32 vcc, 0, v2
	v_mov_b32_e32 v0, s5
	ds_read_b32 v0, v0
	s_cbranch_vccnz .LBB0_350
	v_readlane_b32 s6, v254, 4
	v_readlane_b32 s7, v254, 5
	s_load_dwordx2 s[4:5], s[6:7], 0x0
	s_nop 0
	s_load_dword s6, s[6:7], 0x8
	s_mov_b32 s15, 1
	s_waitcnt lgkmcnt(0)
	s_mul_i32 s13, s5, s4
	s_mul_i32 s13, s13, s6
	s_branch .LBB0_338
